# GEMM core v3 also in EVEN_IN and both OUT projections
# speedup vs baseline: 1.1482x; 1.0174x over previous
.LBB0_659:
	s_and_b32 s1, s46, 0x78
	s_or_b32 s1, s1, s67
	s_waitcnt vmcnt(0)
	s_lshl_b32 s13, s1, 8
	s_lshl_b32 s1, s46, 7
	s_and_b32 s10, s1, 0x380
	s_lshl_b32 s0, s46, 8
	s_and_b32 s0, s0, 0x7800
	s_or_b32 s9, s75, s0
	s_and_b32 s8, s35, 0x380
	s_mov_b32 s19, 0
	s_waitcnt vmcnt(21)
	s_waitcnt vmcnt(20)
	s_waitcnt vmcnt(14)
	s_lshr_b32 s21, s13, 21
	s_lshl_b32 s20, s13, 11
	s_add_u32 s50, s2, s20
	s_addc_u32 s51, s3, s21
	s_add_u32 s52, s50, 0x8000
	s_addc_u32 s53, s51, 0
	s_add_u32 s54, s52, 0x8000
	s_addc_u32 s55, s53, 0
	s_add_u32 s56, s54, 0x8000
	s_addc_u32 s57, s55, 0
	s_lshr_b32 s21, s10, 21
	s_lshl_b32 s20, s10, 11
	s_add_u32 s58, s22, s20
	s_addc_u32 s59, s23, s21
	s_add_u32 s60, s58, 0x8000
	s_addc_u32 s61, s59, 0
	v_lshrrev_b32_e32 v238, 6, v179
	s_nop 0
	v_readfirstlane_b32 s63, v238
	v_and_b32_e32 v239, 63, v179
	v_lshrrev_b32_e32 v240, 3, v239
	v_and_b32_e32 v241, 7, v239
	v_lshrrev_b32_e32 v238, 1, v240
	v_lshrrev_b32_e32 v239, 2, v240
	v_xor_b32_e32 v0, v238, v239
	v_xor_b32_e32 v208, 5, v0
	v_xor_b32_e32 v0, v0, v241
	v_lshlrev_b32_e32 v0, 4, v0
	v_mov_b32_e32 v209, v0
	v_xor_b32_e32 v208, v208, v241
	v_lshlrev_b32_e32 v208, 4, v208
	v_mov_b32_e32 v242, v208
	s_lshl_b32 s81, s63, 6
	v_add_u32_e32 v238, s81, v240
	v_lshl_add_u32 v0, v238, 11, v0
	v_add_u32_e32 v238, 8, v238
	v_lshl_add_u32 v208, v238, 11, v208
	s_lshl_b32 s81, s63, 5
	v_add_u32_e32 v238, s81, v240
	v_lshl_add_u32 v209, v238, 11, v209
	v_add_u32_e32 v238, 8, v238
	v_lshl_add_u32 v242, v238, 11, v242
	v_and_b32_e32 v238, 15, v179
	v_bfe_u32 v239, v179, 4, 2
	v_lshrrev_b32_e32 v240, 1, v238
	v_add_u32_e32 v241, 4, v238
	v_bfe_u32 v241, v241, 3, 1
	v_xor_b32_e32 v240, v240, v241
	v_xor_b32_e32 v239, v239, v240
	v_lshlrev_b32_e32 v239, 4, v239
	v_lshl_add_u32 v245, v238, 7, v239
	s_lshl_b32 s81, s63, 13
	v_add_u32_e32 v243, s81, v245
	v_add_u32_e32 v245, 32768, v245
	v_xor_b32_e32 v244, 64, v243
	v_xor_b32_e32 v246, 64, v245
	s_lshl_b32 s32, s63, 13
	s_lshl_b32 s47, s63, 12
	s_add_u32 s47, s47, 32768
	v_mov_b32_e32 v166, 0
	v_mov_b32_e32 v167, 0
	v_mov_b32_e32 v168, 0
	v_mov_b32_e32 v169, 0
	v_mov_b32_e32 v146, 0
	v_mov_b32_e32 v147, 0
	v_mov_b32_e32 v148, 0
	v_mov_b32_e32 v149, 0
	v_mov_b32_e32 v134, 0
	v_mov_b32_e32 v135, 0
	v_mov_b32_e32 v136, 0
	v_mov_b32_e32 v137, 0
	v_mov_b32_e32 v114, 0
	v_mov_b32_e32 v115, 0
	v_mov_b32_e32 v116, 0
	v_mov_b32_e32 v117, 0
	v_mov_b32_e32 v110, 0
	v_mov_b32_e32 v111, 0
	v_mov_b32_e32 v112, 0
	v_mov_b32_e32 v113, 0
	v_mov_b32_e32 v106, 0
	v_mov_b32_e32 v107, 0
	v_mov_b32_e32 v108, 0
	v_mov_b32_e32 v109, 0
	v_mov_b32_e32 v102, 0
	v_mov_b32_e32 v103, 0
	v_mov_b32_e32 v104, 0
	v_mov_b32_e32 v105, 0
	v_mov_b32_e32 v98, 0
	v_mov_b32_e32 v99, 0
	v_mov_b32_e32 v100, 0
	v_mov_b32_e32 v101, 0
	v_mov_b32_e32 v94, 0
	v_mov_b32_e32 v95, 0
	v_mov_b32_e32 v96, 0
	v_mov_b32_e32 v97, 0
	v_mov_b32_e32 v90, 0
	v_mov_b32_e32 v91, 0
	v_mov_b32_e32 v92, 0
	v_mov_b32_e32 v93, 0
	v_mov_b32_e32 v86, 0
	v_mov_b32_e32 v87, 0
	v_mov_b32_e32 v88, 0
	v_mov_b32_e32 v89, 0
	v_mov_b32_e32 v82, 0
	v_mov_b32_e32 v83, 0
	v_mov_b32_e32 v84, 0
	v_mov_b32_e32 v85, 0
	v_mov_b32_e32 v78, 0
	v_mov_b32_e32 v79, 0
	v_mov_b32_e32 v80, 0
	v_mov_b32_e32 v81, 0
	v_mov_b32_e32 v74, 0
	v_mov_b32_e32 v75, 0
	v_mov_b32_e32 v76, 0
	v_mov_b32_e32 v77, 0
	v_mov_b32_e32 v70, 0
	v_mov_b32_e32 v71, 0
	v_mov_b32_e32 v72, 0
	v_mov_b32_e32 v73, 0
	v_mov_b32_e32 v66, 0
	v_mov_b32_e32 v67, 0
	v_mov_b32_e32 v68, 0
	v_mov_b32_e32 v69, 0
	v_mov_b32_e32 v62, 0
	v_mov_b32_e32 v63, 0
	v_mov_b32_e32 v64, 0
	v_mov_b32_e32 v65, 0
	v_mov_b32_e32 v58, 0
	v_mov_b32_e32 v59, 0
	v_mov_b32_e32 v60, 0
	v_mov_b32_e32 v61, 0
	v_mov_b32_e32 v54, 0
	v_mov_b32_e32 v55, 0
	v_mov_b32_e32 v56, 0
	v_mov_b32_e32 v57, 0
	v_mov_b32_e32 v50, 0
	v_mov_b32_e32 v51, 0
	v_mov_b32_e32 v52, 0
	v_mov_b32_e32 v53, 0
	v_mov_b32_e32 v46, 0
	v_mov_b32_e32 v47, 0
	v_mov_b32_e32 v48, 0
	v_mov_b32_e32 v49, 0
	v_mov_b32_e32 v42, 0
	v_mov_b32_e32 v43, 0
	v_mov_b32_e32 v44, 0
	v_mov_b32_e32 v45, 0
	v_mov_b32_e32 v38, 0
	v_mov_b32_e32 v39, 0
	v_mov_b32_e32 v40, 0
	v_mov_b32_e32 v41, 0
	v_mov_b32_e32 v34, 0
	v_mov_b32_e32 v35, 0
	v_mov_b32_e32 v36, 0
	v_mov_b32_e32 v37, 0
	v_mov_b32_e32 v30, 0
	v_mov_b32_e32 v31, 0
	v_mov_b32_e32 v32, 0
	v_mov_b32_e32 v33, 0
	v_mov_b32_e32 v26, 0
	v_mov_b32_e32 v27, 0
	v_mov_b32_e32 v28, 0
	v_mov_b32_e32 v29, 0
	v_mov_b32_e32 v22, 0
	v_mov_b32_e32 v23, 0
	v_mov_b32_e32 v24, 0
	v_mov_b32_e32 v25, 0
	v_mov_b32_e32 v18, 0
	v_mov_b32_e32 v19, 0
	v_mov_b32_e32 v20, 0
	v_mov_b32_e32 v21, 0
	v_mov_b32_e32 v14, 0
	v_mov_b32_e32 v15, 0
	v_mov_b32_e32 v16, 0
	v_mov_b32_e32 v17, 0
	v_mov_b32_e32 v10, 0
	v_mov_b32_e32 v11, 0
	v_mov_b32_e32 v12, 0
	v_mov_b32_e32 v13, 0
	v_mov_b32_e32 v6, 0
	v_mov_b32_e32 v7, 0
	v_mov_b32_e32 v8, 0
	v_mov_b32_e32 v9, 0
	v_mov_b32_e32 v2, 0
	v_mov_b32_e32 v3, 0
	v_mov_b32_e32 v4, 0
	v_mov_b32_e32 v5, 0
	s_barrier
	s_mov_b32 m0, s32
	s_nop 0
	global_load_lds_dwordx4 v0, s[50:51]
	s_add_u32 m0, s32, 1024
	s_nop 0
	global_load_lds_dwordx4 v208, s[50:51]
	s_add_u32 m0, s32, 2048
	s_nop 0
	global_load_lds_dwordx4 v0, s[52:53]
	s_add_u32 m0, s32, 3072
	s_nop 0
	global_load_lds_dwordx4 v208, s[52:53]
	s_add_u32 m0, s32, 4096
	s_nop 0
	global_load_lds_dwordx4 v0, s[54:55]
	s_add_u32 m0, s32, 5120
	s_nop 0
	global_load_lds_dwordx4 v208, s[54:55]
	s_add_u32 m0, s32, 6144
	s_nop 0
	global_load_lds_dwordx4 v0, s[56:57]
	s_add_u32 m0, s32, 7168
	s_nop 0
	global_load_lds_dwordx4 v208, s[56:57]
	s_mov_b32 m0, s47
	s_nop 0
	global_load_lds_dwordx4 v209, s[58:59]
	s_add_u32 m0, s47, 1024
	s_nop 0
	global_load_lds_dwordx4 v242, s[58:59]
	s_add_u32 m0, s47, 2048
	s_nop 0
	global_load_lds_dwordx4 v209, s[60:61]
	s_add_u32 m0, s47, 3072
	s_nop 0
	global_load_lds_dwordx4 v242, s[60:61]
	s_add_u32 s50, s50, 0x80
	s_addc_u32 s51, s51, 0
	s_add_u32 s52, s52, 0x80
	s_addc_u32 s53, s53, 0
	s_add_u32 s54, s54, 0x80
	s_addc_u32 s55, s55, 0
	s_add_u32 s56, s56, 0x80
	s_addc_u32 s57, s57, 0
	s_add_u32 s58, s58, 0x80
	s_addc_u32 s59, s59, 0
	s_add_u32 s60, s60, 0x80
	s_addc_u32 s61, s61, 0
	s_mov_b32 s49, 15
.Lg3_ood_loop:
	s_waitcnt vmcnt(0)
	s_barrier
	ds_read_b128 v[196:199], v243
	ds_read_b128 v[200:203], v243 offset:2048
	ds_read_b128 v[204:207], v243 offset:4096
	ds_read_b128 v[216:219], v243 offset:6144
	ds_read_b128 v[118:121], v245
	ds_read_b128 v[122:125], v245 offset:2048
	ds_read_b128 v[126:129], v245 offset:4096
	ds_read_b128 v[130:133], v245 offset:6144
	ds_read_b128 v[138:141], v245 offset:8192
	ds_read_b128 v[142:145], v245 offset:10240
	ds_read_b128 v[150:153], v245 offset:12288
	ds_read_b128 v[154:157], v245 offset:14336
	ds_read_b128 v[158:161], v246
	ds_read_b128 v[162:165], v246 offset:2048
	ds_read_b128 v[170:173], v246 offset:4096
	ds_read_b128 v[174:177], v246 offset:6144
	ds_read_b128 v[180:183], v246 offset:8192
	ds_read_b128 v[184:187], v246 offset:10240
	ds_read_b128 v[188:191], v246 offset:12288
	ds_read_b128 v[192:195], v246 offset:14336
	ds_read_b128 v[226:229], v244
	ds_read_b128 v[230:233], v244 offset:2048
	ds_read_b128 v[234:237], v244 offset:4096
	ds_read_b128 v[238:241], v244 offset:6144
	s_waitcnt lgkmcnt(0)
	s_barrier
	s_mov_b32 m0, s32
	s_nop 0
	global_load_lds_dwordx4 v0, s[50:51]
	s_add_u32 m0, s32, 1024
	s_nop 0
	global_load_lds_dwordx4 v208, s[50:51]
	s_add_u32 m0, s32, 2048
	s_nop 0
	global_load_lds_dwordx4 v0, s[52:53]
	s_add_u32 m0, s32, 3072
	s_nop 0
	global_load_lds_dwordx4 v208, s[52:53]
	s_add_u32 m0, s32, 4096
	s_nop 0
	global_load_lds_dwordx4 v0, s[54:55]
	s_add_u32 m0, s32, 5120
	s_nop 0
	global_load_lds_dwordx4 v208, s[54:55]
	s_add_u32 m0, s32, 6144
	s_nop 0
	global_load_lds_dwordx4 v0, s[56:57]
	s_add_u32 m0, s32, 7168
	s_nop 0
	global_load_lds_dwordx4 v208, s[56:57]
	s_mov_b32 m0, s47
	s_nop 0
	global_load_lds_dwordx4 v209, s[58:59]
	s_add_u32 m0, s47, 1024
	s_nop 0
	global_load_lds_dwordx4 v242, s[58:59]
	s_add_u32 m0, s47, 2048
	s_nop 0
	global_load_lds_dwordx4 v209, s[60:61]
	s_add_u32 m0, s47, 3072
	s_nop 0
	global_load_lds_dwordx4 v242, s[60:61]
	s_add_u32 s50, s50, 0x80
	s_addc_u32 s51, s51, 0
	s_add_u32 s52, s52, 0x80
	s_addc_u32 s53, s53, 0
	s_add_u32 s54, s54, 0x80
	s_addc_u32 s55, s55, 0
	s_add_u32 s56, s56, 0x80
	s_addc_u32 s57, s57, 0
	s_add_u32 s58, s58, 0x80
	s_addc_u32 s59, s59, 0
	s_add_u32 s60, s60, 0x80
	s_addc_u32 s61, s61, 0
	v_mfma_f32_16x16x32_bf16 v[166:169], v[118:121], v[196:199], v[166:169]
	v_mfma_f32_16x16x32_bf16 v[94:97], v[118:121], v[200:203], v[94:97]
	v_mfma_f32_16x16x32_bf16 v[62:65], v[118:121], v[204:207], v[62:65]
	v_mfma_f32_16x16x32_bf16 v[30:33], v[118:121], v[216:219], v[30:33]
	v_mfma_f32_16x16x32_bf16 v[146:149], v[122:125], v[196:199], v[146:149]
	v_mfma_f32_16x16x32_bf16 v[90:93], v[122:125], v[200:203], v[90:93]
	v_mfma_f32_16x16x32_bf16 v[58:61], v[122:125], v[204:207], v[58:61]
	v_mfma_f32_16x16x32_bf16 v[26:29], v[122:125], v[216:219], v[26:29]
	v_mfma_f32_16x16x32_bf16 v[134:137], v[126:129], v[196:199], v[134:137]
	v_mfma_f32_16x16x32_bf16 v[86:89], v[126:129], v[200:203], v[86:89]
	v_mfma_f32_16x16x32_bf16 v[54:57], v[126:129], v[204:207], v[54:57]
	v_mfma_f32_16x16x32_bf16 v[22:25], v[126:129], v[216:219], v[22:25]
	v_mfma_f32_16x16x32_bf16 v[114:117], v[130:133], v[196:199], v[114:117]
	v_mfma_f32_16x16x32_bf16 v[82:85], v[130:133], v[200:203], v[82:85]
	v_mfma_f32_16x16x32_bf16 v[50:53], v[130:133], v[204:207], v[50:53]
	v_mfma_f32_16x16x32_bf16 v[18:21], v[130:133], v[216:219], v[18:21]
	v_mfma_f32_16x16x32_bf16 v[110:113], v[138:141], v[196:199], v[110:113]
	v_mfma_f32_16x16x32_bf16 v[78:81], v[138:141], v[200:203], v[78:81]
	v_mfma_f32_16x16x32_bf16 v[46:49], v[138:141], v[204:207], v[46:49]
	v_mfma_f32_16x16x32_bf16 v[14:17], v[138:141], v[216:219], v[14:17]
	v_mfma_f32_16x16x32_bf16 v[106:109], v[142:145], v[196:199], v[106:109]
	v_mfma_f32_16x16x32_bf16 v[74:77], v[142:145], v[200:203], v[74:77]
	v_mfma_f32_16x16x32_bf16 v[42:45], v[142:145], v[204:207], v[42:45]
	v_mfma_f32_16x16x32_bf16 v[10:13], v[142:145], v[216:219], v[10:13]
	v_mfma_f32_16x16x32_bf16 v[102:105], v[150:153], v[196:199], v[102:105]
	v_mfma_f32_16x16x32_bf16 v[70:73], v[150:153], v[200:203], v[70:73]
	v_mfma_f32_16x16x32_bf16 v[38:41], v[150:153], v[204:207], v[38:41]
	v_mfma_f32_16x16x32_bf16 v[6:9], v[150:153], v[216:219], v[6:9]
	v_mfma_f32_16x16x32_bf16 v[98:101], v[154:157], v[196:199], v[98:101]
	v_mfma_f32_16x16x32_bf16 v[66:69], v[154:157], v[200:203], v[66:69]
	v_mfma_f32_16x16x32_bf16 v[34:37], v[154:157], v[204:207], v[34:37]
	v_mfma_f32_16x16x32_bf16 v[2:5], v[154:157], v[216:219], v[2:5]
	v_mfma_f32_16x16x32_bf16 v[166:169], v[158:161], v[226:229], v[166:169]
	v_mfma_f32_16x16x32_bf16 v[94:97], v[158:161], v[230:233], v[94:97]
	v_mfma_f32_16x16x32_bf16 v[62:65], v[158:161], v[234:237], v[62:65]
	v_mfma_f32_16x16x32_bf16 v[30:33], v[158:161], v[238:241], v[30:33]
	v_mfma_f32_16x16x32_bf16 v[146:149], v[162:165], v[226:229], v[146:149]
	v_mfma_f32_16x16x32_bf16 v[90:93], v[162:165], v[230:233], v[90:93]
	v_mfma_f32_16x16x32_bf16 v[58:61], v[162:165], v[234:237], v[58:61]
	v_mfma_f32_16x16x32_bf16 v[26:29], v[162:165], v[238:241], v[26:29]
	v_mfma_f32_16x16x32_bf16 v[134:137], v[170:173], v[226:229], v[134:137]
	v_mfma_f32_16x16x32_bf16 v[86:89], v[170:173], v[230:233], v[86:89]
	v_mfma_f32_16x16x32_bf16 v[54:57], v[170:173], v[234:237], v[54:57]
	v_mfma_f32_16x16x32_bf16 v[22:25], v[170:173], v[238:241], v[22:25]
	v_mfma_f32_16x16x32_bf16 v[114:117], v[174:177], v[226:229], v[114:117]
	v_mfma_f32_16x16x32_bf16 v[82:85], v[174:177], v[230:233], v[82:85]
	v_mfma_f32_16x16x32_bf16 v[50:53], v[174:177], v[234:237], v[50:53]
	v_mfma_f32_16x16x32_bf16 v[18:21], v[174:177], v[238:241], v[18:21]
	v_mfma_f32_16x16x32_bf16 v[110:113], v[180:183], v[226:229], v[110:113]
	v_mfma_f32_16x16x32_bf16 v[78:81], v[180:183], v[230:233], v[78:81]
	v_mfma_f32_16x16x32_bf16 v[46:49], v[180:183], v[234:237], v[46:49]
	v_mfma_f32_16x16x32_bf16 v[14:17], v[180:183], v[238:241], v[14:17]
	v_mfma_f32_16x16x32_bf16 v[106:109], v[184:187], v[226:229], v[106:109]
	v_mfma_f32_16x16x32_bf16 v[74:77], v[184:187], v[230:233], v[74:77]
	v_mfma_f32_16x16x32_bf16 v[42:45], v[184:187], v[234:237], v[42:45]
	v_mfma_f32_16x16x32_bf16 v[10:13], v[184:187], v[238:241], v[10:13]
	v_mfma_f32_16x16x32_bf16 v[102:105], v[188:191], v[226:229], v[102:105]
	v_mfma_f32_16x16x32_bf16 v[70:73], v[188:191], v[230:233], v[70:73]
	v_mfma_f32_16x16x32_bf16 v[38:41], v[188:191], v[234:237], v[38:41]
	v_mfma_f32_16x16x32_bf16 v[6:9], v[188:191], v[238:241], v[6:9]
	v_mfma_f32_16x16x32_bf16 v[98:101], v[192:195], v[226:229], v[98:101]
	v_mfma_f32_16x16x32_bf16 v[66:69], v[192:195], v[230:233], v[66:69]
	v_mfma_f32_16x16x32_bf16 v[34:37], v[192:195], v[234:237], v[34:37]
	v_mfma_f32_16x16x32_bf16 v[2:5], v[192:195], v[238:241], v[2:5]
	s_sub_u32 s49, s49, 1
	s_cmp_lg_u32 s49, 0
	s_cbranch_scc1 .Lg3_ood_loop
	s_waitcnt vmcnt(0)
	s_barrier
	ds_read_b128 v[196:199], v243
	ds_read_b128 v[200:203], v243 offset:2048
	ds_read_b128 v[204:207], v243 offset:4096
	ds_read_b128 v[216:219], v243 offset:6144
	ds_read_b128 v[118:121], v245
	ds_read_b128 v[122:125], v245 offset:2048
	ds_read_b128 v[126:129], v245 offset:4096
	ds_read_b128 v[130:133], v245 offset:6144
	ds_read_b128 v[138:141], v245 offset:8192
	ds_read_b128 v[142:145], v245 offset:10240
	ds_read_b128 v[150:153], v245 offset:12288
	ds_read_b128 v[154:157], v245 offset:14336
	ds_read_b128 v[158:161], v246
	ds_read_b128 v[162:165], v246 offset:2048
	ds_read_b128 v[170:173], v246 offset:4096
	ds_read_b128 v[174:177], v246 offset:6144
	ds_read_b128 v[180:183], v246 offset:8192
	ds_read_b128 v[184:187], v246 offset:10240
	ds_read_b128 v[188:191], v246 offset:12288
	ds_read_b128 v[192:195], v246 offset:14336
	ds_read_b128 v[226:229], v244
	ds_read_b128 v[230:233], v244 offset:2048
	ds_read_b128 v[234:237], v244 offset:4096
	ds_read_b128 v[238:241], v244 offset:6144
	s_waitcnt lgkmcnt(0)
	s_barrier
	v_mfma_f32_16x16x32_bf16 v[166:169], v[118:121], v[196:199], v[166:169]
	v_mfma_f32_16x16x32_bf16 v[94:97], v[118:121], v[200:203], v[94:97]
	v_mfma_f32_16x16x32_bf16 v[62:65], v[118:121], v[204:207], v[62:65]
	v_mfma_f32_16x16x32_bf16 v[30:33], v[118:121], v[216:219], v[30:33]
	v_mfma_f32_16x16x32_bf16 v[146:149], v[122:125], v[196:199], v[146:149]
	v_mfma_f32_16x16x32_bf16 v[90:93], v[122:125], v[200:203], v[90:93]
	v_mfma_f32_16x16x32_bf16 v[58:61], v[122:125], v[204:207], v[58:61]
	v_mfma_f32_16x16x32_bf16 v[26:29], v[122:125], v[216:219], v[26:29]
	v_mfma_f32_16x16x32_bf16 v[134:137], v[126:129], v[196:199], v[134:137]
	v_mfma_f32_16x16x32_bf16 v[86:89], v[126:129], v[200:203], v[86:89]
	v_mfma_f32_16x16x32_bf16 v[54:57], v[126:129], v[204:207], v[54:57]
	v_mfma_f32_16x16x32_bf16 v[22:25], v[126:129], v[216:219], v[22:25]
	v_mfma_f32_16x16x32_bf16 v[114:117], v[130:133], v[196:199], v[114:117]
	v_mfma_f32_16x16x32_bf16 v[82:85], v[130:133], v[200:203], v[82:85]
	v_mfma_f32_16x16x32_bf16 v[50:53], v[130:133], v[204:207], v[50:53]
	v_mfma_f32_16x16x32_bf16 v[18:21], v[130:133], v[216:219], v[18:21]
	v_mfma_f32_16x16x32_bf16 v[110:113], v[138:141], v[196:199], v[110:113]
	v_mfma_f32_16x16x32_bf16 v[78:81], v[138:141], v[200:203], v[78:81]
	v_mfma_f32_16x16x32_bf16 v[46:49], v[138:141], v[204:207], v[46:49]
	v_mfma_f32_16x16x32_bf16 v[14:17], v[138:141], v[216:219], v[14:17]
	v_mfma_f32_16x16x32_bf16 v[106:109], v[142:145], v[196:199], v[106:109]
	v_mfma_f32_16x16x32_bf16 v[74:77], v[142:145], v[200:203], v[74:77]
	v_mfma_f32_16x16x32_bf16 v[42:45], v[142:145], v[204:207], v[42:45]
	v_mfma_f32_16x16x32_bf16 v[10:13], v[142:145], v[216:219], v[10:13]
	v_mfma_f32_16x16x32_bf16 v[102:105], v[150:153], v[196:199], v[102:105]
	v_mfma_f32_16x16x32_bf16 v[70:73], v[150:153], v[200:203], v[70:73]
	v_mfma_f32_16x16x32_bf16 v[38:41], v[150:153], v[204:207], v[38:41]
	v_mfma_f32_16x16x32_bf16 v[6:9], v[150:153], v[216:219], v[6:9]
	v_mfma_f32_16x16x32_bf16 v[98:101], v[154:157], v[196:199], v[98:101]
	v_mfma_f32_16x16x32_bf16 v[66:69], v[154:157], v[200:203], v[66:69]
	v_mfma_f32_16x16x32_bf16 v[34:37], v[154:157], v[204:207], v[34:37]
	v_mfma_f32_16x16x32_bf16 v[2:5], v[154:157], v[216:219], v[2:5]
	v_mfma_f32_16x16x32_bf16 v[166:169], v[158:161], v[226:229], v[166:169]
	v_mfma_f32_16x16x32_bf16 v[94:97], v[158:161], v[230:233], v[94:97]
	v_mfma_f32_16x16x32_bf16 v[62:65], v[158:161], v[234:237], v[62:65]
	v_mfma_f32_16x16x32_bf16 v[30:33], v[158:161], v[238:241], v[30:33]
	v_mfma_f32_16x16x32_bf16 v[146:149], v[162:165], v[226:229], v[146:149]
	v_mfma_f32_16x16x32_bf16 v[90:93], v[162:165], v[230:233], v[90:93]
	v_mfma_f32_16x16x32_bf16 v[58:61], v[162:165], v[234:237], v[58:61]
	v_mfma_f32_16x16x32_bf16 v[26:29], v[162:165], v[238:241], v[26:29]
	v_mfma_f32_16x16x32_bf16 v[134:137], v[170:173], v[226:229], v[134:137]
	v_mfma_f32_16x16x32_bf16 v[86:89], v[170:173], v[230:233], v[86:89]
	v_mfma_f32_16x16x32_bf16 v[54:57], v[170:173], v[234:237], v[54:57]
	v_mfma_f32_16x16x32_bf16 v[22:25], v[170:173], v[238:241], v[22:25]
	v_mfma_f32_16x16x32_bf16 v[114:117], v[174:177], v[226:229], v[114:117]
	v_mfma_f32_16x16x32_bf16 v[82:85], v[174:177], v[230:233], v[82:85]
	v_mfma_f32_16x16x32_bf16 v[50:53], v[174:177], v[234:237], v[50:53]
	v_mfma_f32_16x16x32_bf16 v[18:21], v[174:177], v[238:241], v[18:21]
	v_mfma_f32_16x16x32_bf16 v[110:113], v[180:183], v[226:229], v[110:113]
	v_mfma_f32_16x16x32_bf16 v[78:81], v[180:183], v[230:233], v[78:81]
	v_mfma_f32_16x16x32_bf16 v[46:49], v[180:183], v[234:237], v[46:49]
	v_mfma_f32_16x16x32_bf16 v[14:17], v[180:183], v[238:241], v[14:17]
	v_mfma_f32_16x16x32_bf16 v[106:109], v[184:187], v[226:229], v[106:109]
	v_mfma_f32_16x16x32_bf16 v[74:77], v[184:187], v[230:233], v[74:77]
	v_mfma_f32_16x16x32_bf16 v[42:45], v[184:187], v[234:237], v[42:45]
	v_mfma_f32_16x16x32_bf16 v[10:13], v[184:187], v[238:241], v[10:13]
	v_mfma_f32_16x16x32_bf16 v[102:105], v[188:191], v[226:229], v[102:105]
	v_mfma_f32_16x16x32_bf16 v[70:73], v[188:191], v[230:233], v[70:73]
	v_mfma_f32_16x16x32_bf16 v[38:41], v[188:191], v[234:237], v[38:41]
	v_mfma_f32_16x16x32_bf16 v[6:9], v[188:191], v[238:241], v[6:9]
	v_mfma_f32_16x16x32_bf16 v[98:101], v[192:195], v[226:229], v[98:101]
	v_mfma_f32_16x16x32_bf16 v[66:69], v[192:195], v[230:233], v[66:69]
	v_mfma_f32_16x16x32_bf16 v[34:37], v[192:195], v[234:237], v[34:37]
	v_mfma_f32_16x16x32_bf16 v[2:5], v[192:195], v[238:241], v[2:5]
	s_branch .LBB0_663

.LBB0_840:
	s_and_b32 s0, s38, 0xff
	s_mulk_i32 s0, 0xf1
	s_lshr_b32 s0, s0, 12
	s_lshl_b32 s1, s0, 11
	s_waitcnt vmcnt(0)
	s_or_b32 s8, s1, s75
	s_mul_i32 s0, s0, 17
	s_sub_i32 s0, s38, s0
	s_and_b32 s45, s0, 0xff
	s_lshl_b32 s9, s45, 7
	s_mov_b32 s10, 0
	s_mov_b64 s[0:1], s[86:87]
	s_waitcnt vmcnt(21)
	s_waitcnt vmcnt(20)
	s_waitcnt vmcnt(15)
	s_waitcnt vmcnt(12)
	s_lshr_b32 s21, s8, 21
	s_lshl_b32 s20, s8, 11
	s_add_u32 s50, s70, s20
	s_addc_u32 s51, s71, s21
	s_add_u32 s52, s50, 0x8000
	s_addc_u32 s53, s51, 0
	s_add_u32 s54, s52, 0x8000
	s_addc_u32 s55, s53, 0
	s_add_u32 s56, s54, 0x8000
	s_addc_u32 s57, s55, 0
	s_lshr_b32 s21, s9, 21
	s_lshl_b32 s20, s9, 11
	s_add_u32 s58, s22, s20
	s_addc_u32 s59, s23, s21
	s_add_u32 s60, s58, 0x8000
	s_addc_u32 s61, s59, 0
	v_lshrrev_b32_e32 v246, 6, v179
	s_nop 0
	v_readfirstlane_b32 s63, v246
	v_and_b32_e32 v247, 63, v179
	v_lshrrev_b32_e32 v248, 3, v247
	v_and_b32_e32 v249, 7, v247
	v_lshrrev_b32_e32 v246, 1, v248
	v_lshrrev_b32_e32 v247, 2, v248
	v_xor_b32_e32 v0, v246, v247
	v_xor_b32_e32 v114, 5, v0
	v_xor_b32_e32 v0, v0, v249
	v_lshlrev_b32_e32 v0, 4, v0
	v_mov_b32_e32 v115, v0
	v_xor_b32_e32 v114, v114, v249
	v_lshlrev_b32_e32 v114, 4, v114
	v_mov_b32_e32 v116, v114
	s_lshl_b32 s81, s63, 6
	v_add_u32_e32 v246, s81, v248
	v_lshl_add_u32 v0, v246, 11, v0
	v_add_u32_e32 v246, 8, v246
	v_lshl_add_u32 v114, v246, 11, v114
	s_lshl_b32 s81, s63, 5
	v_add_u32_e32 v246, s81, v248
	v_lshl_add_u32 v115, v246, 11, v115
	v_add_u32_e32 v246, 8, v246
	v_lshl_add_u32 v116, v246, 11, v116
	v_and_b32_e32 v246, 15, v179
	v_bfe_u32 v247, v179, 4, 2
	v_lshrrev_b32_e32 v248, 1, v246
	v_add_u32_e32 v249, 4, v246
	v_bfe_u32 v249, v249, 3, 1
	v_xor_b32_e32 v248, v248, v249
	v_xor_b32_e32 v247, v247, v248
	v_lshlrev_b32_e32 v247, 4, v247
	v_lshl_add_u32 v126, v246, 7, v247
	s_lshl_b32 s81, s63, 13
	v_add_u32_e32 v122, s81, v126
	v_add_u32_e32 v126, 32768, v126
	v_xor_b32_e32 v124, 64, v122
	v_xor_b32_e32 v128, 64, v126
	s_lshl_b32 s46, s63, 13
	s_lshl_b32 s47, s63, 12
	s_add_u32 s47, s47, 32768
	v_mov_b32_e32 v174, 0
	v_mov_b32_e32 v175, 0
	v_mov_b32_e32 v176, 0
	v_mov_b32_e32 v177, 0
	v_mov_b32_e32 v162, 0
	v_mov_b32_e32 v163, 0
	v_mov_b32_e32 v164, 0
	v_mov_b32_e32 v165, 0
	v_mov_b32_e32 v150, 0
	v_mov_b32_e32 v151, 0
	v_mov_b32_e32 v152, 0
	v_mov_b32_e32 v153, 0
	v_mov_b32_e32 v130, 0
	v_mov_b32_e32 v131, 0
	v_mov_b32_e32 v132, 0
	v_mov_b32_e32 v133, 0
	v_mov_b32_e32 v118, 0
	v_mov_b32_e32 v119, 0
	v_mov_b32_e32 v120, 0
	v_mov_b32_e32 v121, 0
	v_mov_b32_e32 v106, 0
	v_mov_b32_e32 v107, 0
	v_mov_b32_e32 v108, 0
	v_mov_b32_e32 v109, 0
	v_mov_b32_e32 v102, 0
	v_mov_b32_e32 v103, 0
	v_mov_b32_e32 v104, 0
	v_mov_b32_e32 v105, 0
	v_mov_b32_e32 v98, 0
	v_mov_b32_e32 v99, 0
	v_mov_b32_e32 v100, 0
	v_mov_b32_e32 v101, 0
	v_mov_b32_e32 v94, 0
	v_mov_b32_e32 v95, 0
	v_mov_b32_e32 v96, 0
	v_mov_b32_e32 v97, 0
	v_mov_b32_e32 v90, 0
	v_mov_b32_e32 v91, 0
	v_mov_b32_e32 v92, 0
	v_mov_b32_e32 v93, 0
	v_mov_b32_e32 v86, 0
	v_mov_b32_e32 v87, 0
	v_mov_b32_e32 v88, 0
	v_mov_b32_e32 v89, 0
	v_mov_b32_e32 v82, 0
	v_mov_b32_e32 v83, 0
	v_mov_b32_e32 v84, 0
	v_mov_b32_e32 v85, 0
	v_mov_b32_e32 v78, 0
	v_mov_b32_e32 v79, 0
	v_mov_b32_e32 v80, 0
	v_mov_b32_e32 v81, 0
	v_mov_b32_e32 v74, 0
	v_mov_b32_e32 v75, 0
	v_mov_b32_e32 v76, 0
	v_mov_b32_e32 v77, 0
	v_mov_b32_e32 v70, 0
	v_mov_b32_e32 v71, 0
	v_mov_b32_e32 v72, 0
	v_mov_b32_e32 v73, 0
	v_mov_b32_e32 v66, 0
	v_mov_b32_e32 v67, 0
	v_mov_b32_e32 v68, 0
	v_mov_b32_e32 v69, 0
	v_mov_b32_e32 v62, 0
	v_mov_b32_e32 v63, 0
	v_mov_b32_e32 v64, 0
	v_mov_b32_e32 v65, 0
	v_mov_b32_e32 v58, 0
	v_mov_b32_e32 v59, 0
	v_mov_b32_e32 v60, 0
	v_mov_b32_e32 v61, 0
	v_mov_b32_e32 v54, 0
	v_mov_b32_e32 v55, 0
	v_mov_b32_e32 v56, 0
	v_mov_b32_e32 v57, 0
	v_mov_b32_e32 v50, 0
	v_mov_b32_e32 v51, 0
	v_mov_b32_e32 v52, 0
	v_mov_b32_e32 v53, 0
	v_mov_b32_e32 v46, 0
	v_mov_b32_e32 v47, 0
	v_mov_b32_e32 v48, 0
	v_mov_b32_e32 v49, 0
	v_mov_b32_e32 v42, 0
	v_mov_b32_e32 v43, 0
	v_mov_b32_e32 v44, 0
	v_mov_b32_e32 v45, 0
	v_mov_b32_e32 v38, 0
	v_mov_b32_e32 v39, 0
	v_mov_b32_e32 v40, 0
	v_mov_b32_e32 v41, 0
	v_mov_b32_e32 v34, 0
	v_mov_b32_e32 v35, 0
	v_mov_b32_e32 v36, 0
	v_mov_b32_e32 v37, 0
	v_mov_b32_e32 v30, 0
	v_mov_b32_e32 v31, 0
	v_mov_b32_e32 v32, 0
	v_mov_b32_e32 v33, 0
	v_mov_b32_e32 v26, 0
	v_mov_b32_e32 v27, 0
	v_mov_b32_e32 v28, 0
	v_mov_b32_e32 v29, 0
	v_mov_b32_e32 v22, 0
	v_mov_b32_e32 v23, 0
	v_mov_b32_e32 v24, 0
	v_mov_b32_e32 v25, 0
	v_mov_b32_e32 v18, 0
	v_mov_b32_e32 v19, 0
	v_mov_b32_e32 v20, 0
	v_mov_b32_e32 v21, 0
	v_mov_b32_e32 v14, 0
	v_mov_b32_e32 v15, 0
	v_mov_b32_e32 v16, 0
	v_mov_b32_e32 v17, 0
	v_mov_b32_e32 v10, 0
	v_mov_b32_e32 v11, 0
	v_mov_b32_e32 v12, 0
	v_mov_b32_e32 v13, 0
	v_mov_b32_e32 v6, 0
	v_mov_b32_e32 v7, 0
	v_mov_b32_e32 v8, 0
	v_mov_b32_e32 v9, 0
	v_mov_b32_e32 v2, 0
	v_mov_b32_e32 v3, 0
	v_mov_b32_e32 v4, 0
	v_mov_b32_e32 v5, 0
	s_barrier
	s_mov_b32 m0, s46
	s_nop 0
	global_load_lds_dwordx4 v0, s[50:51]
	s_add_u32 m0, s46, 1024
	s_nop 0
	global_load_lds_dwordx4 v114, s[50:51]
	s_add_u32 m0, s46, 2048
	s_nop 0
	global_load_lds_dwordx4 v0, s[52:53]
	s_add_u32 m0, s46, 3072
	s_nop 0
	global_load_lds_dwordx4 v114, s[52:53]
	s_add_u32 m0, s46, 4096
	s_nop 0
	global_load_lds_dwordx4 v0, s[54:55]
	s_add_u32 m0, s46, 5120
	s_nop 0
	global_load_lds_dwordx4 v114, s[54:55]
	s_add_u32 m0, s46, 6144
	s_nop 0
	global_load_lds_dwordx4 v0, s[56:57]
	s_add_u32 m0, s46, 7168
	s_nop 0
	global_load_lds_dwordx4 v114, s[56:57]
	s_mov_b32 m0, s47
	s_nop 0
	global_load_lds_dwordx4 v115, s[58:59]
	s_add_u32 m0, s47, 1024
	s_nop 0
	global_load_lds_dwordx4 v116, s[58:59]
	s_add_u32 m0, s47, 2048
	s_nop 0
	global_load_lds_dwordx4 v115, s[60:61]
	s_add_u32 m0, s47, 3072
	s_nop 0
	global_load_lds_dwordx4 v116, s[60:61]
	s_add_u32 s50, s50, 0x80
	s_addc_u32 s51, s51, 0
	s_add_u32 s52, s52, 0x80
	s_addc_u32 s53, s53, 0
	s_add_u32 s54, s54, 0x80
	s_addc_u32 s55, s55, 0
	s_add_u32 s56, s56, 0x80
	s_addc_u32 s57, s57, 0
	s_add_u32 s58, s58, 0x80
	s_addc_u32 s59, s59, 0
	s_add_u32 s60, s60, 0x80
	s_addc_u32 s61, s61, 0
	s_mov_b32 s49, 15
.Lg3_ein_loop:
	s_waitcnt vmcnt(0)
	s_barrier
	ds_read_b128 v[226:229], v122
	ds_read_b128 v[230:233], v122 offset:2048
	ds_read_b128 v[234:237], v122 offset:4096
	ds_read_b128 v[238:241], v122 offset:6144
	ds_read_b128 v[110:113], v126
	ds_read_b128 v[138:141], v126 offset:2048
	ds_read_b128 v[142:145], v126 offset:4096
	ds_read_b128 v[146:149], v126 offset:6144
	ds_read_b128 v[154:157], v126 offset:8192
	ds_read_b128 v[158:161], v126 offset:10240
	ds_read_b128 v[166:169], v126 offset:12288
	ds_read_b128 v[170:173], v126 offset:14336
	s_waitcnt lgkmcnt(7)
	v_mfma_f32_16x16x32_bf16 v[174:177], v[110:113], v[226:229], v[174:177]
	v_mfma_f32_16x16x32_bf16 v[94:97], v[110:113], v[230:233], v[94:97]
	v_mfma_f32_16x16x32_bf16 v[62:65], v[110:113], v[234:237], v[62:65]
	v_mfma_f32_16x16x32_bf16 v[30:33], v[110:113], v[238:241], v[30:33]
	s_waitcnt lgkmcnt(6)
	v_mfma_f32_16x16x32_bf16 v[162:165], v[138:141], v[226:229], v[162:165]
	v_mfma_f32_16x16x32_bf16 v[90:93], v[138:141], v[230:233], v[90:93]
	v_mfma_f32_16x16x32_bf16 v[58:61], v[138:141], v[234:237], v[58:61]
	v_mfma_f32_16x16x32_bf16 v[26:29], v[138:141], v[238:241], v[26:29]
	ds_read_b128 v[180:183], v128
	ds_read_b128 v[184:187], v128 offset:2048
	ds_read_b128 v[188:191], v128 offset:4096
	ds_read_b128 v[192:195], v128 offset:6144
	ds_read_b128 v[196:199], v128 offset:8192
	ds_read_b128 v[200:203], v128 offset:10240
	ds_read_b128 v[204:207], v128 offset:12288
	ds_read_b128 v[216:219], v128 offset:14336
	ds_read_b128 v[242:245], v124
	ds_read_b128 v[246:249], v124 offset:2048
	ds_read_b128 v[138:141], v124 offset:4096
	ds_read_b128 v[110:113], v124 offset:6144
	s_waitcnt lgkmcnt(0)
	s_barrier
	s_mov_b32 m0, s46
	s_nop 0
	global_load_lds_dwordx4 v0, s[50:51]
	s_add_u32 m0, s46, 1024
	s_nop 0
	global_load_lds_dwordx4 v114, s[50:51]
	s_add_u32 m0, s46, 2048
	s_nop 0
	global_load_lds_dwordx4 v0, s[52:53]
	s_add_u32 m0, s46, 3072
	s_nop 0
	global_load_lds_dwordx4 v114, s[52:53]
	s_add_u32 m0, s46, 4096
	s_nop 0
	global_load_lds_dwordx4 v0, s[54:55]
	s_add_u32 m0, s46, 5120
	s_nop 0
	global_load_lds_dwordx4 v114, s[54:55]
	s_add_u32 m0, s46, 6144
	s_nop 0
	global_load_lds_dwordx4 v0, s[56:57]
	s_add_u32 m0, s46, 7168
	s_nop 0
	global_load_lds_dwordx4 v114, s[56:57]
	s_mov_b32 m0, s47
	s_nop 0
	global_load_lds_dwordx4 v115, s[58:59]
	s_add_u32 m0, s47, 1024
	s_nop 0
	global_load_lds_dwordx4 v116, s[58:59]
	s_add_u32 m0, s47, 2048
	s_nop 0
	global_load_lds_dwordx4 v115, s[60:61]
	s_add_u32 m0, s47, 3072
	s_nop 0
	global_load_lds_dwordx4 v116, s[60:61]
	s_add_u32 s50, s50, 0x80
	s_addc_u32 s51, s51, 0
	s_add_u32 s52, s52, 0x80
	s_addc_u32 s53, s53, 0
	s_add_u32 s54, s54, 0x80
	s_addc_u32 s55, s55, 0
	s_add_u32 s56, s56, 0x80
	s_addc_u32 s57, s57, 0
	s_add_u32 s58, s58, 0x80
	s_addc_u32 s59, s59, 0
	s_add_u32 s60, s60, 0x80
	s_addc_u32 s61, s61, 0
	v_mfma_f32_16x16x32_bf16 v[150:153], v[142:145], v[226:229], v[150:153]
	v_mfma_f32_16x16x32_bf16 v[86:89], v[142:145], v[230:233], v[86:89]
	v_mfma_f32_16x16x32_bf16 v[54:57], v[142:145], v[234:237], v[54:57]
	v_mfma_f32_16x16x32_bf16 v[22:25], v[142:145], v[238:241], v[22:25]
	v_mfma_f32_16x16x32_bf16 v[130:133], v[146:149], v[226:229], v[130:133]
	v_mfma_f32_16x16x32_bf16 v[82:85], v[146:149], v[230:233], v[82:85]
	v_mfma_f32_16x16x32_bf16 v[50:53], v[146:149], v[234:237], v[50:53]
	v_mfma_f32_16x16x32_bf16 v[18:21], v[146:149], v[238:241], v[18:21]
	v_mfma_f32_16x16x32_bf16 v[118:121], v[154:157], v[226:229], v[118:121]
	v_mfma_f32_16x16x32_bf16 v[78:81], v[154:157], v[230:233], v[78:81]
	v_mfma_f32_16x16x32_bf16 v[46:49], v[154:157], v[234:237], v[46:49]
	v_mfma_f32_16x16x32_bf16 v[14:17], v[154:157], v[238:241], v[14:17]
	v_mfma_f32_16x16x32_bf16 v[106:109], v[158:161], v[226:229], v[106:109]
	v_mfma_f32_16x16x32_bf16 v[74:77], v[158:161], v[230:233], v[74:77]
	v_mfma_f32_16x16x32_bf16 v[42:45], v[158:161], v[234:237], v[42:45]
	v_mfma_f32_16x16x32_bf16 v[10:13], v[158:161], v[238:241], v[10:13]
	v_mfma_f32_16x16x32_bf16 v[102:105], v[166:169], v[226:229], v[102:105]
	v_mfma_f32_16x16x32_bf16 v[70:73], v[166:169], v[230:233], v[70:73]
	v_mfma_f32_16x16x32_bf16 v[38:41], v[166:169], v[234:237], v[38:41]
	v_mfma_f32_16x16x32_bf16 v[6:9], v[166:169], v[238:241], v[6:9]
	v_mfma_f32_16x16x32_bf16 v[98:101], v[170:173], v[226:229], v[98:101]
	v_mfma_f32_16x16x32_bf16 v[66:69], v[170:173], v[230:233], v[66:69]
	v_mfma_f32_16x16x32_bf16 v[34:37], v[170:173], v[234:237], v[34:37]
	v_mfma_f32_16x16x32_bf16 v[2:5], v[170:173], v[238:241], v[2:5]
	v_mfma_f32_16x16x32_bf16 v[174:177], v[180:183], v[242:245], v[174:177]
	v_mfma_f32_16x16x32_bf16 v[94:97], v[180:183], v[246:249], v[94:97]
	v_mfma_f32_16x16x32_bf16 v[62:65], v[180:183], v[138:141], v[62:65]
	v_mfma_f32_16x16x32_bf16 v[30:33], v[180:183], v[110:113], v[30:33]
	v_mfma_f32_16x16x32_bf16 v[162:165], v[184:187], v[242:245], v[162:165]
	v_mfma_f32_16x16x32_bf16 v[90:93], v[184:187], v[246:249], v[90:93]
	v_mfma_f32_16x16x32_bf16 v[58:61], v[184:187], v[138:141], v[58:61]
	v_mfma_f32_16x16x32_bf16 v[26:29], v[184:187], v[110:113], v[26:29]
	v_mfma_f32_16x16x32_bf16 v[150:153], v[188:191], v[242:245], v[150:153]
	v_mfma_f32_16x16x32_bf16 v[86:89], v[188:191], v[246:249], v[86:89]
	v_mfma_f32_16x16x32_bf16 v[54:57], v[188:191], v[138:141], v[54:57]
	v_mfma_f32_16x16x32_bf16 v[22:25], v[188:191], v[110:113], v[22:25]
	v_mfma_f32_16x16x32_bf16 v[130:133], v[192:195], v[242:245], v[130:133]
	v_mfma_f32_16x16x32_bf16 v[82:85], v[192:195], v[246:249], v[82:85]
	v_mfma_f32_16x16x32_bf16 v[50:53], v[192:195], v[138:141], v[50:53]
	v_mfma_f32_16x16x32_bf16 v[18:21], v[192:195], v[110:113], v[18:21]
	v_mfma_f32_16x16x32_bf16 v[118:121], v[196:199], v[242:245], v[118:121]
	v_mfma_f32_16x16x32_bf16 v[78:81], v[196:199], v[246:249], v[78:81]
	v_mfma_f32_16x16x32_bf16 v[46:49], v[196:199], v[138:141], v[46:49]
	v_mfma_f32_16x16x32_bf16 v[14:17], v[196:199], v[110:113], v[14:17]
	v_mfma_f32_16x16x32_bf16 v[106:109], v[200:203], v[242:245], v[106:109]
	v_mfma_f32_16x16x32_bf16 v[74:77], v[200:203], v[246:249], v[74:77]
	v_mfma_f32_16x16x32_bf16 v[42:45], v[200:203], v[138:141], v[42:45]
	v_mfma_f32_16x16x32_bf16 v[10:13], v[200:203], v[110:113], v[10:13]
	v_mfma_f32_16x16x32_bf16 v[102:105], v[204:207], v[242:245], v[102:105]
	v_mfma_f32_16x16x32_bf16 v[70:73], v[204:207], v[246:249], v[70:73]
	v_mfma_f32_16x16x32_bf16 v[38:41], v[204:207], v[138:141], v[38:41]
	v_mfma_f32_16x16x32_bf16 v[6:9], v[204:207], v[110:113], v[6:9]
	v_mfma_f32_16x16x32_bf16 v[98:101], v[216:219], v[242:245], v[98:101]
	v_mfma_f32_16x16x32_bf16 v[66:69], v[216:219], v[246:249], v[66:69]
	v_mfma_f32_16x16x32_bf16 v[34:37], v[216:219], v[138:141], v[34:37]
	v_mfma_f32_16x16x32_bf16 v[2:5], v[216:219], v[110:113], v[2:5]
	s_sub_u32 s49, s49, 1
	s_cmp_lg_u32 s49, 0
	s_cbranch_scc1 .Lg3_ein_loop
	s_waitcnt vmcnt(0)
	s_barrier
	ds_read_b128 v[226:229], v122
	ds_read_b128 v[230:233], v122 offset:2048
	ds_read_b128 v[234:237], v122 offset:4096
	ds_read_b128 v[238:241], v122 offset:6144
	ds_read_b128 v[110:113], v126
	ds_read_b128 v[138:141], v126 offset:2048
	ds_read_b128 v[142:145], v126 offset:4096
	ds_read_b128 v[146:149], v126 offset:6144
	ds_read_b128 v[154:157], v126 offset:8192
	ds_read_b128 v[158:161], v126 offset:10240
	ds_read_b128 v[166:169], v126 offset:12288
	ds_read_b128 v[170:173], v126 offset:14336
	s_waitcnt lgkmcnt(7)
	v_mfma_f32_16x16x32_bf16 v[174:177], v[110:113], v[226:229], v[174:177]
	v_mfma_f32_16x16x32_bf16 v[94:97], v[110:113], v[230:233], v[94:97]
	v_mfma_f32_16x16x32_bf16 v[62:65], v[110:113], v[234:237], v[62:65]
	v_mfma_f32_16x16x32_bf16 v[30:33], v[110:113], v[238:241], v[30:33]
	s_waitcnt lgkmcnt(6)
	v_mfma_f32_16x16x32_bf16 v[162:165], v[138:141], v[226:229], v[162:165]
	v_mfma_f32_16x16x32_bf16 v[90:93], v[138:141], v[230:233], v[90:93]
	v_mfma_f32_16x16x32_bf16 v[58:61], v[138:141], v[234:237], v[58:61]
	v_mfma_f32_16x16x32_bf16 v[26:29], v[138:141], v[238:241], v[26:29]
	ds_read_b128 v[180:183], v128
	ds_read_b128 v[184:187], v128 offset:2048
	ds_read_b128 v[188:191], v128 offset:4096
	ds_read_b128 v[192:195], v128 offset:6144
	ds_read_b128 v[196:199], v128 offset:8192
	ds_read_b128 v[200:203], v128 offset:10240
	ds_read_b128 v[204:207], v128 offset:12288
	ds_read_b128 v[216:219], v128 offset:14336
	ds_read_b128 v[242:245], v124
	ds_read_b128 v[246:249], v124 offset:2048
	ds_read_b128 v[138:141], v124 offset:4096
	ds_read_b128 v[110:113], v124 offset:6144
	s_waitcnt lgkmcnt(0)
	s_barrier
	v_mfma_f32_16x16x32_bf16 v[150:153], v[142:145], v[226:229], v[150:153]
	v_mfma_f32_16x16x32_bf16 v[86:89], v[142:145], v[230:233], v[86:89]
	v_mfma_f32_16x16x32_bf16 v[54:57], v[142:145], v[234:237], v[54:57]
	v_mfma_f32_16x16x32_bf16 v[22:25], v[142:145], v[238:241], v[22:25]
	v_mfma_f32_16x16x32_bf16 v[130:133], v[146:149], v[226:229], v[130:133]
	v_mfma_f32_16x16x32_bf16 v[82:85], v[146:149], v[230:233], v[82:85]
	v_mfma_f32_16x16x32_bf16 v[50:53], v[146:149], v[234:237], v[50:53]
	v_mfma_f32_16x16x32_bf16 v[18:21], v[146:149], v[238:241], v[18:21]
	v_mfma_f32_16x16x32_bf16 v[118:121], v[154:157], v[226:229], v[118:121]
	v_mfma_f32_16x16x32_bf16 v[78:81], v[154:157], v[230:233], v[78:81]
	v_mfma_f32_16x16x32_bf16 v[46:49], v[154:157], v[234:237], v[46:49]
	v_mfma_f32_16x16x32_bf16 v[14:17], v[154:157], v[238:241], v[14:17]
	v_mfma_f32_16x16x32_bf16 v[106:109], v[158:161], v[226:229], v[106:109]
	v_mfma_f32_16x16x32_bf16 v[74:77], v[158:161], v[230:233], v[74:77]
	v_mfma_f32_16x16x32_bf16 v[42:45], v[158:161], v[234:237], v[42:45]
	v_mfma_f32_16x16x32_bf16 v[10:13], v[158:161], v[238:241], v[10:13]
	v_mfma_f32_16x16x32_bf16 v[102:105], v[166:169], v[226:229], v[102:105]
	v_mfma_f32_16x16x32_bf16 v[70:73], v[166:169], v[230:233], v[70:73]
	v_mfma_f32_16x16x32_bf16 v[38:41], v[166:169], v[234:237], v[38:41]
	v_mfma_f32_16x16x32_bf16 v[6:9], v[166:169], v[238:241], v[6:9]
	v_mfma_f32_16x16x32_bf16 v[98:101], v[170:173], v[226:229], v[98:101]
	v_mfma_f32_16x16x32_bf16 v[66:69], v[170:173], v[230:233], v[66:69]
	v_mfma_f32_16x16x32_bf16 v[34:37], v[170:173], v[234:237], v[34:37]
	v_mfma_f32_16x16x32_bf16 v[2:5], v[170:173], v[238:241], v[2:5]
	v_mfma_f32_16x16x32_bf16 v[174:177], v[180:183], v[242:245], v[174:177]
	v_mfma_f32_16x16x32_bf16 v[94:97], v[180:183], v[246:249], v[94:97]
	v_mfma_f32_16x16x32_bf16 v[62:65], v[180:183], v[138:141], v[62:65]
	v_mfma_f32_16x16x32_bf16 v[30:33], v[180:183], v[110:113], v[30:33]
	v_mfma_f32_16x16x32_bf16 v[162:165], v[184:187], v[242:245], v[162:165]
	v_mfma_f32_16x16x32_bf16 v[90:93], v[184:187], v[246:249], v[90:93]
	v_mfma_f32_16x16x32_bf16 v[58:61], v[184:187], v[138:141], v[58:61]
	v_mfma_f32_16x16x32_bf16 v[26:29], v[184:187], v[110:113], v[26:29]
	v_mfma_f32_16x16x32_bf16 v[150:153], v[188:191], v[242:245], v[150:153]
	v_mfma_f32_16x16x32_bf16 v[86:89], v[188:191], v[246:249], v[86:89]
	v_mfma_f32_16x16x32_bf16 v[54:57], v[188:191], v[138:141], v[54:57]
	v_mfma_f32_16x16x32_bf16 v[22:25], v[188:191], v[110:113], v[22:25]
	v_mfma_f32_16x16x32_bf16 v[130:133], v[192:195], v[242:245], v[130:133]
	v_mfma_f32_16x16x32_bf16 v[82:85], v[192:195], v[246:249], v[82:85]
	v_mfma_f32_16x16x32_bf16 v[50:53], v[192:195], v[138:141], v[50:53]
	v_mfma_f32_16x16x32_bf16 v[18:21], v[192:195], v[110:113], v[18:21]
	v_mfma_f32_16x16x32_bf16 v[118:121], v[196:199], v[242:245], v[118:121]
	v_mfma_f32_16x16x32_bf16 v[78:81], v[196:199], v[246:249], v[78:81]
	v_mfma_f32_16x16x32_bf16 v[46:49], v[196:199], v[138:141], v[46:49]
	v_mfma_f32_16x16x32_bf16 v[14:17], v[196:199], v[110:113], v[14:17]
	v_mfma_f32_16x16x32_bf16 v[106:109], v[200:203], v[242:245], v[106:109]
	v_mfma_f32_16x16x32_bf16 v[74:77], v[200:203], v[246:249], v[74:77]
	v_mfma_f32_16x16x32_bf16 v[42:45], v[200:203], v[138:141], v[42:45]
	v_mfma_f32_16x16x32_bf16 v[10:13], v[200:203], v[110:113], v[10:13]
	v_mfma_f32_16x16x32_bf16 v[102:105], v[204:207], v[242:245], v[102:105]
	v_mfma_f32_16x16x32_bf16 v[70:73], v[204:207], v[246:249], v[70:73]
	v_mfma_f32_16x16x32_bf16 v[38:41], v[204:207], v[138:141], v[38:41]
	v_mfma_f32_16x16x32_bf16 v[6:9], v[204:207], v[110:113], v[6:9]
	v_mfma_f32_16x16x32_bf16 v[98:101], v[216:219], v[242:245], v[98:101]
	v_mfma_f32_16x16x32_bf16 v[66:69], v[216:219], v[246:249], v[66:69]
	v_mfma_f32_16x16x32_bf16 v[34:37], v[216:219], v[138:141], v[34:37]
	v_mfma_f32_16x16x32_bf16 v[2:5], v[216:219], v[110:113], v[2:5]
	s_branch .LBB0_844

.LBB0_1635:
	s_and_b32 s1, s34, 0x78
	s_or_b32 s1, s1, s67
	s_waitcnt vmcnt(0)
	s_lshl_b32 s13, s1, 8
	s_lshl_b32 s1, s34, 7
	s_and_b32 s10, s1, 0x380
	s_lshl_b32 s0, s34, 8
	s_and_b32 s0, s0, 0x7800
	s_or_b32 s9, s75, s0
	s_and_b32 s8, s23, 0x380
	s_mov_b32 s19, 0
	s_lshr_b32 s21, s13, 21
	s_lshl_b32 s20, s13, 11
	s_add_u32 s50, s2, s20
	s_addc_u32 s51, s3, s21
	s_add_u32 s52, s50, 0x8000
	s_addc_u32 s53, s51, 0
	s_add_u32 s54, s52, 0x8000
	s_addc_u32 s55, s53, 0
	s_add_u32 s56, s54, 0x8000
	s_addc_u32 s57, s55, 0
	s_lshr_b32 s21, s10, 21
	s_lshl_b32 s20, s10, 11
	s_add_u32 s58, s6, s20
	s_addc_u32 s59, s7, s21
	s_add_u32 s60, s58, 0x8000
	s_addc_u32 s61, s59, 0
	v_lshrrev_b32_e32 v238, 6, v179
	s_nop 0
	v_readfirstlane_b32 s63, v238
	v_and_b32_e32 v239, 63, v179
	v_lshrrev_b32_e32 v240, 3, v239
	v_and_b32_e32 v241, 7, v239
	v_lshrrev_b32_e32 v238, 1, v240
	v_lshrrev_b32_e32 v239, 2, v240
	v_xor_b32_e32 v0, v238, v239
	v_xor_b32_e32 v208, 5, v0
	v_xor_b32_e32 v0, v0, v241
	v_lshlrev_b32_e32 v0, 4, v0
	v_mov_b32_e32 v209, v0
	v_xor_b32_e32 v208, v208, v241
	v_lshlrev_b32_e32 v208, 4, v208
	v_mov_b32_e32 v242, v208
	s_lshl_b32 s81, s63, 6
	v_add_u32_e32 v238, s81, v240
	v_lshl_add_u32 v0, v238, 11, v0
	v_add_u32_e32 v238, 8, v238
	v_lshl_add_u32 v208, v238, 11, v208
	s_lshl_b32 s81, s63, 5
	v_add_u32_e32 v238, s81, v240
	v_lshl_add_u32 v209, v238, 11, v209
	v_add_u32_e32 v238, 8, v238
	v_lshl_add_u32 v242, v238, 11, v242
	v_and_b32_e32 v238, 15, v179
	v_bfe_u32 v239, v179, 4, 2
	v_lshrrev_b32_e32 v240, 1, v238
	v_add_u32_e32 v241, 4, v238
	v_bfe_u32 v241, v241, 3, 1
	v_xor_b32_e32 v240, v240, v241
	v_xor_b32_e32 v239, v239, v240
	v_lshlrev_b32_e32 v239, 4, v239
	v_lshl_add_u32 v245, v238, 7, v239
	s_lshl_b32 s81, s63, 13
	v_add_u32_e32 v243, s81, v245
	v_add_u32_e32 v245, 32768, v245
	v_xor_b32_e32 v244, 64, v243
	v_xor_b32_e32 v246, 64, v245
	s_lshl_b32 s46, s63, 13
	s_lshl_b32 s47, s63, 12
	s_add_u32 s47, s47, 32768
	v_mov_b32_e32 v166, 0
	v_mov_b32_e32 v167, 0
	v_mov_b32_e32 v168, 0
	v_mov_b32_e32 v169, 0
	v_mov_b32_e32 v146, 0
	v_mov_b32_e32 v147, 0
	v_mov_b32_e32 v148, 0
	v_mov_b32_e32 v149, 0
	v_mov_b32_e32 v130, 0
	v_mov_b32_e32 v131, 0
	v_mov_b32_e32 v132, 0
	v_mov_b32_e32 v133, 0
	v_mov_b32_e32 v114, 0
	v_mov_b32_e32 v115, 0
	v_mov_b32_e32 v116, 0
	v_mov_b32_e32 v117, 0
	v_mov_b32_e32 v110, 0
	v_mov_b32_e32 v111, 0
	v_mov_b32_e32 v112, 0
	v_mov_b32_e32 v113, 0
	v_mov_b32_e32 v106, 0
	v_mov_b32_e32 v107, 0
	v_mov_b32_e32 v108, 0
	v_mov_b32_e32 v109, 0
	v_mov_b32_e32 v102, 0
	v_mov_b32_e32 v103, 0
	v_mov_b32_e32 v104, 0
	v_mov_b32_e32 v105, 0
	v_mov_b32_e32 v98, 0
	v_mov_b32_e32 v99, 0
	v_mov_b32_e32 v100, 0
	v_mov_b32_e32 v101, 0
	v_mov_b32_e32 v94, 0
	v_mov_b32_e32 v95, 0
	v_mov_b32_e32 v96, 0
	v_mov_b32_e32 v97, 0
	v_mov_b32_e32 v90, 0
	v_mov_b32_e32 v91, 0
	v_mov_b32_e32 v92, 0
	v_mov_b32_e32 v93, 0
	v_mov_b32_e32 v86, 0
	v_mov_b32_e32 v87, 0
	v_mov_b32_e32 v88, 0
	v_mov_b32_e32 v89, 0
	v_mov_b32_e32 v82, 0
	v_mov_b32_e32 v83, 0
	v_mov_b32_e32 v84, 0
	v_mov_b32_e32 v85, 0
	v_mov_b32_e32 v78, 0
	v_mov_b32_e32 v79, 0
	v_mov_b32_e32 v80, 0
	v_mov_b32_e32 v81, 0
	v_mov_b32_e32 v74, 0
	v_mov_b32_e32 v75, 0
	v_mov_b32_e32 v76, 0
	v_mov_b32_e32 v77, 0
	v_mov_b32_e32 v70, 0
	v_mov_b32_e32 v71, 0
	v_mov_b32_e32 v72, 0
	v_mov_b32_e32 v73, 0
	v_mov_b32_e32 v66, 0
	v_mov_b32_e32 v67, 0
	v_mov_b32_e32 v68, 0
	v_mov_b32_e32 v69, 0
	v_mov_b32_e32 v62, 0
	v_mov_b32_e32 v63, 0
	v_mov_b32_e32 v64, 0
	v_mov_b32_e32 v65, 0
	v_mov_b32_e32 v58, 0
	v_mov_b32_e32 v59, 0
	v_mov_b32_e32 v60, 0
	v_mov_b32_e32 v61, 0
	v_mov_b32_e32 v54, 0
	v_mov_b32_e32 v55, 0
	v_mov_b32_e32 v56, 0
	v_mov_b32_e32 v57, 0
	v_mov_b32_e32 v50, 0
	v_mov_b32_e32 v51, 0
	v_mov_b32_e32 v52, 0
	v_mov_b32_e32 v53, 0
	v_mov_b32_e32 v46, 0
	v_mov_b32_e32 v47, 0
	v_mov_b32_e32 v48, 0
	v_mov_b32_e32 v49, 0
	v_mov_b32_e32 v42, 0
	v_mov_b32_e32 v43, 0
	v_mov_b32_e32 v44, 0
	v_mov_b32_e32 v45, 0
	v_mov_b32_e32 v38, 0
	v_mov_b32_e32 v39, 0
	v_mov_b32_e32 v40, 0
	v_mov_b32_e32 v41, 0
	v_mov_b32_e32 v34, 0
	v_mov_b32_e32 v35, 0
	v_mov_b32_e32 v36, 0
	v_mov_b32_e32 v37, 0
	v_mov_b32_e32 v30, 0
	v_mov_b32_e32 v31, 0
	v_mov_b32_e32 v32, 0
	v_mov_b32_e32 v33, 0
	v_mov_b32_e32 v26, 0
	v_mov_b32_e32 v27, 0
	v_mov_b32_e32 v28, 0
	v_mov_b32_e32 v29, 0
	v_mov_b32_e32 v22, 0
	v_mov_b32_e32 v23, 0
	v_mov_b32_e32 v24, 0
	v_mov_b32_e32 v25, 0
	v_mov_b32_e32 v18, 0
	v_mov_b32_e32 v19, 0
	v_mov_b32_e32 v20, 0
	v_mov_b32_e32 v21, 0
	v_mov_b32_e32 v14, 0
	v_mov_b32_e32 v15, 0
	v_mov_b32_e32 v16, 0
	v_mov_b32_e32 v17, 0
	v_mov_b32_e32 v10, 0
	v_mov_b32_e32 v11, 0
	v_mov_b32_e32 v12, 0
	v_mov_b32_e32 v13, 0
	v_mov_b32_e32 v6, 0
	v_mov_b32_e32 v7, 0
	v_mov_b32_e32 v8, 0
	v_mov_b32_e32 v9, 0
	v_mov_b32_e32 v2, 0
	v_mov_b32_e32 v3, 0
	v_mov_b32_e32 v4, 0
	v_mov_b32_e32 v5, 0
	s_barrier
	s_mov_b32 m0, s46
	s_nop 0
	global_load_lds_dwordx4 v0, s[50:51]
	s_add_u32 m0, s46, 1024
	s_nop 0
	global_load_lds_dwordx4 v208, s[50:51]
	s_add_u32 m0, s46, 2048
	s_nop 0
	global_load_lds_dwordx4 v0, s[52:53]
	s_add_u32 m0, s46, 3072
	s_nop 0
	global_load_lds_dwordx4 v208, s[52:53]
	s_add_u32 m0, s46, 4096
	s_nop 0
	global_load_lds_dwordx4 v0, s[54:55]
	s_add_u32 m0, s46, 5120
	s_nop 0
	global_load_lds_dwordx4 v208, s[54:55]
	s_add_u32 m0, s46, 6144
	s_nop 0
	global_load_lds_dwordx4 v0, s[56:57]
	s_add_u32 m0, s46, 7168
	s_nop 0
	global_load_lds_dwordx4 v208, s[56:57]
	s_mov_b32 m0, s47
	s_nop 0
	global_load_lds_dwordx4 v209, s[58:59]
	s_add_u32 m0, s47, 1024
	s_nop 0
	global_load_lds_dwordx4 v242, s[58:59]
	s_add_u32 m0, s47, 2048
	s_nop 0
	global_load_lds_dwordx4 v209, s[60:61]
	s_add_u32 m0, s47, 3072
	s_nop 0
	global_load_lds_dwordx4 v242, s[60:61]
	s_add_u32 s50, s50, 0x80
	s_addc_u32 s51, s51, 0
	s_add_u32 s52, s52, 0x80
	s_addc_u32 s53, s53, 0
	s_add_u32 s54, s54, 0x80
	s_addc_u32 s55, s55, 0
	s_add_u32 s56, s56, 0x80
	s_addc_u32 s57, s57, 0
	s_add_u32 s58, s58, 0x80
	s_addc_u32 s59, s59, 0
	s_add_u32 s60, s60, 0x80
	s_addc_u32 s61, s61, 0
	s_mov_b32 s49, 15
.Lg3_oev_loop:
	s_waitcnt vmcnt(0)
	s_barrier
	ds_read_b128 v[196:199], v243
	ds_read_b128 v[200:203], v243 offset:2048
	ds_read_b128 v[204:207], v243 offset:4096
	ds_read_b128 v[216:219], v243 offset:6144
	ds_read_b128 v[118:121], v245
	ds_read_b128 v[122:125], v245 offset:2048
	ds_read_b128 v[126:129], v245 offset:4096
	ds_read_b128 v[134:137], v245 offset:6144
	ds_read_b128 v[138:141], v245 offset:8192
	ds_read_b128 v[142:145], v245 offset:10240
	ds_read_b128 v[150:153], v245 offset:12288
	ds_read_b128 v[154:157], v245 offset:14336
	ds_read_b128 v[158:161], v246
	ds_read_b128 v[162:165], v246 offset:2048
	ds_read_b128 v[170:173], v246 offset:4096
	ds_read_b128 v[174:177], v246 offset:6144
	ds_read_b128 v[180:183], v246 offset:8192
	ds_read_b128 v[184:187], v246 offset:10240
	ds_read_b128 v[188:191], v246 offset:12288
	ds_read_b128 v[192:195], v246 offset:14336
	ds_read_b128 v[226:229], v244
	ds_read_b128 v[230:233], v244 offset:2048
	ds_read_b128 v[234:237], v244 offset:4096
	ds_read_b128 v[238:241], v244 offset:6144
	s_waitcnt lgkmcnt(0)
	s_barrier
	s_mov_b32 m0, s46
	s_nop 0
	global_load_lds_dwordx4 v0, s[50:51]
	s_add_u32 m0, s46, 1024
	s_nop 0
	global_load_lds_dwordx4 v208, s[50:51]
	s_add_u32 m0, s46, 2048
	s_nop 0
	global_load_lds_dwordx4 v0, s[52:53]
	s_add_u32 m0, s46, 3072
	s_nop 0
	global_load_lds_dwordx4 v208, s[52:53]
	s_add_u32 m0, s46, 4096
	s_nop 0
	global_load_lds_dwordx4 v0, s[54:55]
	s_add_u32 m0, s46, 5120
	s_nop 0
	global_load_lds_dwordx4 v208, s[54:55]
	s_add_u32 m0, s46, 6144
	s_nop 0
	global_load_lds_dwordx4 v0, s[56:57]
	s_add_u32 m0, s46, 7168
	s_nop 0
	global_load_lds_dwordx4 v208, s[56:57]
	s_mov_b32 m0, s47
	s_nop 0
	global_load_lds_dwordx4 v209, s[58:59]
	s_add_u32 m0, s47, 1024
	s_nop 0
	global_load_lds_dwordx4 v242, s[58:59]
	s_add_u32 m0, s47, 2048
	s_nop 0
	global_load_lds_dwordx4 v209, s[60:61]
	s_add_u32 m0, s47, 3072
	s_nop 0
	global_load_lds_dwordx4 v242, s[60:61]
	s_add_u32 s50, s50, 0x80
	s_addc_u32 s51, s51, 0
	s_add_u32 s52, s52, 0x80
	s_addc_u32 s53, s53, 0
	s_add_u32 s54, s54, 0x80
	s_addc_u32 s55, s55, 0
	s_add_u32 s56, s56, 0x80
	s_addc_u32 s57, s57, 0
	s_add_u32 s58, s58, 0x80
	s_addc_u32 s59, s59, 0
	s_add_u32 s60, s60, 0x80
	s_addc_u32 s61, s61, 0
	v_mfma_f32_16x16x32_bf16 v[166:169], v[118:121], v[196:199], v[166:169]
	v_mfma_f32_16x16x32_bf16 v[94:97], v[118:121], v[200:203], v[94:97]
	v_mfma_f32_16x16x32_bf16 v[62:65], v[118:121], v[204:207], v[62:65]
	v_mfma_f32_16x16x32_bf16 v[30:33], v[118:121], v[216:219], v[30:33]
	v_mfma_f32_16x16x32_bf16 v[146:149], v[122:125], v[196:199], v[146:149]
	v_mfma_f32_16x16x32_bf16 v[90:93], v[122:125], v[200:203], v[90:93]
	v_mfma_f32_16x16x32_bf16 v[58:61], v[122:125], v[204:207], v[58:61]
	v_mfma_f32_16x16x32_bf16 v[26:29], v[122:125], v[216:219], v[26:29]
	v_mfma_f32_16x16x32_bf16 v[130:133], v[126:129], v[196:199], v[130:133]
	v_mfma_f32_16x16x32_bf16 v[86:89], v[126:129], v[200:203], v[86:89]
	v_mfma_f32_16x16x32_bf16 v[54:57], v[126:129], v[204:207], v[54:57]
	v_mfma_f32_16x16x32_bf16 v[22:25], v[126:129], v[216:219], v[22:25]
	v_mfma_f32_16x16x32_bf16 v[114:117], v[134:137], v[196:199], v[114:117]
	v_mfma_f32_16x16x32_bf16 v[82:85], v[134:137], v[200:203], v[82:85]
	v_mfma_f32_16x16x32_bf16 v[50:53], v[134:137], v[204:207], v[50:53]
	v_mfma_f32_16x16x32_bf16 v[18:21], v[134:137], v[216:219], v[18:21]
	v_mfma_f32_16x16x32_bf16 v[110:113], v[138:141], v[196:199], v[110:113]
	v_mfma_f32_16x16x32_bf16 v[78:81], v[138:141], v[200:203], v[78:81]
	v_mfma_f32_16x16x32_bf16 v[46:49], v[138:141], v[204:207], v[46:49]
	v_mfma_f32_16x16x32_bf16 v[14:17], v[138:141], v[216:219], v[14:17]
	v_mfma_f32_16x16x32_bf16 v[106:109], v[142:145], v[196:199], v[106:109]
	v_mfma_f32_16x16x32_bf16 v[74:77], v[142:145], v[200:203], v[74:77]
	v_mfma_f32_16x16x32_bf16 v[42:45], v[142:145], v[204:207], v[42:45]
	v_mfma_f32_16x16x32_bf16 v[10:13], v[142:145], v[216:219], v[10:13]
	v_mfma_f32_16x16x32_bf16 v[102:105], v[150:153], v[196:199], v[102:105]
	v_mfma_f32_16x16x32_bf16 v[70:73], v[150:153], v[200:203], v[70:73]
	v_mfma_f32_16x16x32_bf16 v[38:41], v[150:153], v[204:207], v[38:41]
	v_mfma_f32_16x16x32_bf16 v[6:9], v[150:153], v[216:219], v[6:9]
	v_mfma_f32_16x16x32_bf16 v[98:101], v[154:157], v[196:199], v[98:101]
	v_mfma_f32_16x16x32_bf16 v[66:69], v[154:157], v[200:203], v[66:69]
	v_mfma_f32_16x16x32_bf16 v[34:37], v[154:157], v[204:207], v[34:37]
	v_mfma_f32_16x16x32_bf16 v[2:5], v[154:157], v[216:219], v[2:5]
	v_mfma_f32_16x16x32_bf16 v[166:169], v[158:161], v[226:229], v[166:169]
	v_mfma_f32_16x16x32_bf16 v[94:97], v[158:161], v[230:233], v[94:97]
	v_mfma_f32_16x16x32_bf16 v[62:65], v[158:161], v[234:237], v[62:65]
	v_mfma_f32_16x16x32_bf16 v[30:33], v[158:161], v[238:241], v[30:33]
	v_mfma_f32_16x16x32_bf16 v[146:149], v[162:165], v[226:229], v[146:149]
	v_mfma_f32_16x16x32_bf16 v[90:93], v[162:165], v[230:233], v[90:93]
	v_mfma_f32_16x16x32_bf16 v[58:61], v[162:165], v[234:237], v[58:61]
	v_mfma_f32_16x16x32_bf16 v[26:29], v[162:165], v[238:241], v[26:29]
	v_mfma_f32_16x16x32_bf16 v[130:133], v[170:173], v[226:229], v[130:133]
	v_mfma_f32_16x16x32_bf16 v[86:89], v[170:173], v[230:233], v[86:89]
	v_mfma_f32_16x16x32_bf16 v[54:57], v[170:173], v[234:237], v[54:57]
	v_mfma_f32_16x16x32_bf16 v[22:25], v[170:173], v[238:241], v[22:25]
	v_mfma_f32_16x16x32_bf16 v[114:117], v[174:177], v[226:229], v[114:117]
	v_mfma_f32_16x16x32_bf16 v[82:85], v[174:177], v[230:233], v[82:85]
	v_mfma_f32_16x16x32_bf16 v[50:53], v[174:177], v[234:237], v[50:53]
	v_mfma_f32_16x16x32_bf16 v[18:21], v[174:177], v[238:241], v[18:21]
	v_mfma_f32_16x16x32_bf16 v[110:113], v[180:183], v[226:229], v[110:113]
	v_mfma_f32_16x16x32_bf16 v[78:81], v[180:183], v[230:233], v[78:81]
	v_mfma_f32_16x16x32_bf16 v[46:49], v[180:183], v[234:237], v[46:49]
	v_mfma_f32_16x16x32_bf16 v[14:17], v[180:183], v[238:241], v[14:17]
	v_mfma_f32_16x16x32_bf16 v[106:109], v[184:187], v[226:229], v[106:109]
	v_mfma_f32_16x16x32_bf16 v[74:77], v[184:187], v[230:233], v[74:77]
	v_mfma_f32_16x16x32_bf16 v[42:45], v[184:187], v[234:237], v[42:45]
	v_mfma_f32_16x16x32_bf16 v[10:13], v[184:187], v[238:241], v[10:13]
	v_mfma_f32_16x16x32_bf16 v[102:105], v[188:191], v[226:229], v[102:105]
	v_mfma_f32_16x16x32_bf16 v[70:73], v[188:191], v[230:233], v[70:73]
	v_mfma_f32_16x16x32_bf16 v[38:41], v[188:191], v[234:237], v[38:41]
	v_mfma_f32_16x16x32_bf16 v[6:9], v[188:191], v[238:241], v[6:9]
	v_mfma_f32_16x16x32_bf16 v[98:101], v[192:195], v[226:229], v[98:101]
	v_mfma_f32_16x16x32_bf16 v[66:69], v[192:195], v[230:233], v[66:69]
	v_mfma_f32_16x16x32_bf16 v[34:37], v[192:195], v[234:237], v[34:37]
	v_mfma_f32_16x16x32_bf16 v[2:5], v[192:195], v[238:241], v[2:5]
	s_sub_u32 s49, s49, 1
	s_cmp_lg_u32 s49, 0
	s_cbranch_scc1 .Lg3_oev_loop
	s_waitcnt vmcnt(0)
	s_barrier
	ds_read_b128 v[196:199], v243
	ds_read_b128 v[200:203], v243 offset:2048
	ds_read_b128 v[204:207], v243 offset:4096
	ds_read_b128 v[216:219], v243 offset:6144
	ds_read_b128 v[118:121], v245
	ds_read_b128 v[122:125], v245 offset:2048
	ds_read_b128 v[126:129], v245 offset:4096
	ds_read_b128 v[134:137], v245 offset:6144
	ds_read_b128 v[138:141], v245 offset:8192
	ds_read_b128 v[142:145], v245 offset:10240
	ds_read_b128 v[150:153], v245 offset:12288
	ds_read_b128 v[154:157], v245 offset:14336
	ds_read_b128 v[158:161], v246
	ds_read_b128 v[162:165], v246 offset:2048
	ds_read_b128 v[170:173], v246 offset:4096
	ds_read_b128 v[174:177], v246 offset:6144
	ds_read_b128 v[180:183], v246 offset:8192
	ds_read_b128 v[184:187], v246 offset:10240
	ds_read_b128 v[188:191], v246 offset:12288
	ds_read_b128 v[192:195], v246 offset:14336
	ds_read_b128 v[226:229], v244
	ds_read_b128 v[230:233], v244 offset:2048
	ds_read_b128 v[234:237], v244 offset:4096
	ds_read_b128 v[238:241], v244 offset:6144
	s_waitcnt lgkmcnt(0)
	s_barrier
	v_mfma_f32_16x16x32_bf16 v[166:169], v[118:121], v[196:199], v[166:169]
	v_mfma_f32_16x16x32_bf16 v[94:97], v[118:121], v[200:203], v[94:97]
	v_mfma_f32_16x16x32_bf16 v[62:65], v[118:121], v[204:207], v[62:65]
	v_mfma_f32_16x16x32_bf16 v[30:33], v[118:121], v[216:219], v[30:33]
	v_mfma_f32_16x16x32_bf16 v[146:149], v[122:125], v[196:199], v[146:149]
	v_mfma_f32_16x16x32_bf16 v[90:93], v[122:125], v[200:203], v[90:93]
	v_mfma_f32_16x16x32_bf16 v[58:61], v[122:125], v[204:207], v[58:61]
	v_mfma_f32_16x16x32_bf16 v[26:29], v[122:125], v[216:219], v[26:29]
	v_mfma_f32_16x16x32_bf16 v[130:133], v[126:129], v[196:199], v[130:133]
	v_mfma_f32_16x16x32_bf16 v[86:89], v[126:129], v[200:203], v[86:89]
	v_mfma_f32_16x16x32_bf16 v[54:57], v[126:129], v[204:207], v[54:57]
	v_mfma_f32_16x16x32_bf16 v[22:25], v[126:129], v[216:219], v[22:25]
	v_mfma_f32_16x16x32_bf16 v[114:117], v[134:137], v[196:199], v[114:117]
	v_mfma_f32_16x16x32_bf16 v[82:85], v[134:137], v[200:203], v[82:85]
	v_mfma_f32_16x16x32_bf16 v[50:53], v[134:137], v[204:207], v[50:53]
	v_mfma_f32_16x16x32_bf16 v[18:21], v[134:137], v[216:219], v[18:21]
	v_mfma_f32_16x16x32_bf16 v[110:113], v[138:141], v[196:199], v[110:113]
	v_mfma_f32_16x16x32_bf16 v[78:81], v[138:141], v[200:203], v[78:81]
	v_mfma_f32_16x16x32_bf16 v[46:49], v[138:141], v[204:207], v[46:49]
	v_mfma_f32_16x16x32_bf16 v[14:17], v[138:141], v[216:219], v[14:17]
	v_mfma_f32_16x16x32_bf16 v[106:109], v[142:145], v[196:199], v[106:109]
	v_mfma_f32_16x16x32_bf16 v[74:77], v[142:145], v[200:203], v[74:77]
	v_mfma_f32_16x16x32_bf16 v[42:45], v[142:145], v[204:207], v[42:45]
	v_mfma_f32_16x16x32_bf16 v[10:13], v[142:145], v[216:219], v[10:13]
	v_mfma_f32_16x16x32_bf16 v[102:105], v[150:153], v[196:199], v[102:105]
	v_mfma_f32_16x16x32_bf16 v[70:73], v[150:153], v[200:203], v[70:73]
	v_mfma_f32_16x16x32_bf16 v[38:41], v[150:153], v[204:207], v[38:41]
	v_mfma_f32_16x16x32_bf16 v[6:9], v[150:153], v[216:219], v[6:9]
	v_mfma_f32_16x16x32_bf16 v[98:101], v[154:157], v[196:199], v[98:101]
	v_mfma_f32_16x16x32_bf16 v[66:69], v[154:157], v[200:203], v[66:69]
	v_mfma_f32_16x16x32_bf16 v[34:37], v[154:157], v[204:207], v[34:37]
	v_mfma_f32_16x16x32_bf16 v[2:5], v[154:157], v[216:219], v[2:5]
	v_mfma_f32_16x16x32_bf16 v[166:169], v[158:161], v[226:229], v[166:169]
	v_mfma_f32_16x16x32_bf16 v[94:97], v[158:161], v[230:233], v[94:97]
	v_mfma_f32_16x16x32_bf16 v[62:65], v[158:161], v[234:237], v[62:65]
	v_mfma_f32_16x16x32_bf16 v[30:33], v[158:161], v[238:241], v[30:33]
	v_mfma_f32_16x16x32_bf16 v[146:149], v[162:165], v[226:229], v[146:149]
	v_mfma_f32_16x16x32_bf16 v[90:93], v[162:165], v[230:233], v[90:93]
	v_mfma_f32_16x16x32_bf16 v[58:61], v[162:165], v[234:237], v[58:61]
	v_mfma_f32_16x16x32_bf16 v[26:29], v[162:165], v[238:241], v[26:29]
	v_mfma_f32_16x16x32_bf16 v[130:133], v[170:173], v[226:229], v[130:133]
	v_mfma_f32_16x16x32_bf16 v[86:89], v[170:173], v[230:233], v[86:89]
	v_mfma_f32_16x16x32_bf16 v[54:57], v[170:173], v[234:237], v[54:57]
	v_mfma_f32_16x16x32_bf16 v[22:25], v[170:173], v[238:241], v[22:25]
	v_mfma_f32_16x16x32_bf16 v[114:117], v[174:177], v[226:229], v[114:117]
	v_mfma_f32_16x16x32_bf16 v[82:85], v[174:177], v[230:233], v[82:85]
	v_mfma_f32_16x16x32_bf16 v[50:53], v[174:177], v[234:237], v[50:53]
	v_mfma_f32_16x16x32_bf16 v[18:21], v[174:177], v[238:241], v[18:21]
	v_mfma_f32_16x16x32_bf16 v[110:113], v[180:183], v[226:229], v[110:113]
	v_mfma_f32_16x16x32_bf16 v[78:81], v[180:183], v[230:233], v[78:81]
	v_mfma_f32_16x16x32_bf16 v[46:49], v[180:183], v[234:237], v[46:49]
	v_mfma_f32_16x16x32_bf16 v[14:17], v[180:183], v[238:241], v[14:17]
	v_mfma_f32_16x16x32_bf16 v[106:109], v[184:187], v[226:229], v[106:109]
	v_mfma_f32_16x16x32_bf16 v[74:77], v[184:187], v[230:233], v[74:77]
	v_mfma_f32_16x16x32_bf16 v[42:45], v[184:187], v[234:237], v[42:45]
	v_mfma_f32_16x16x32_bf16 v[10:13], v[184:187], v[238:241], v[10:13]
	v_mfma_f32_16x16x32_bf16 v[102:105], v[188:191], v[226:229], v[102:105]
	v_mfma_f32_16x16x32_bf16 v[70:73], v[188:191], v[230:233], v[70:73]
	v_mfma_f32_16x16x32_bf16 v[38:41], v[188:191], v[234:237], v[38:41]
	v_mfma_f32_16x16x32_bf16 v[6:9], v[188:191], v[238:241], v[6:9]
	v_mfma_f32_16x16x32_bf16 v[98:101], v[192:195], v[226:229], v[98:101]
	v_mfma_f32_16x16x32_bf16 v[66:69], v[192:195], v[230:233], v[66:69]
	v_mfma_f32_16x16x32_bf16 v[34:37], v[192:195], v[234:237], v[34:37]
	v_mfma_f32_16x16x32_bf16 v[2:5], v[192:195], v[238:241], v[2:5]
	s_branch .LBB0_1639
